# hand-written K-prep loop (rope/weights hoisted, DPP reductions, 18 row-pairs per wave) on top of pipelined A-attention
# speedup vs baseline: 1.0205x; 1.0012x over previous
; __device__ __forceinline__ void prep_k_pair(const Params& p, int l, int pair, int lane, const u32x4 rawin) {
;     const int row = 2 * pair + (lane >> 5), slot = (lane >> 3) & 3, mixer = slot >> 1, hh = slot & 1, dc = lane & 7;
;     const bool isctx = row >= MLAT; const int b = isctx ? (row - MLAT) >> 8 : row >> 11; const int t = isctx ? (row - MLAT) & 255 : row & 2047; const int pos = isctx ? t : 256 + t;
;     const float* ct = (const float*)(p.ws + WS_ROPE);
;     float v[8]; unpack8(rawin, v);
;     float ss = 0.f;
; #pragma unroll
;     for (int j = 0; j < 8; ++j) ss += v[j] * v[j];
;     ss += __shfl_xor(ss, 1); ss += __shfl_xor(ss, 2); ss += __shfl_xor(ss, 4);
;     const float rstd = rsqrtf(ss * (1.0f / 64.0f) + 1e-6f);
;     const float* wn = (mixer ? p.kn_c : p.kn_a) + l * 64 + 8 * dc;
;     { const f32x4 w0 = *(const f32x4*)wn, w1 = *(const f32x4*)(wn + 4);
;       v[0] *= rstd * w0.x; v[1] *= rstd * w0.y; v[2] *= rstd * w0.z; v[3] *= rstd * w0.w; v[4] *= rstd * w1.x; v[5] *= rstd * w1.y; v[6] *= rstd * w1.z; v[7] *= rstd * w1.w; }
;     if (!isctx) {
;         const int half = dc >> 2, f0 = 8 * (dc & 1); const bool isA = (dc & 2) == 0;
;         const float* cp = ct + (size_t)t * 32 + half * 16 + f0; const float* sp = cp + 2048 * 32;
;         const f32x4 c0 = *(const f32x4*)cp, c1 = *(const f32x4*)(cp + 4), s0 = *(const f32x4*)sp, s1 = *(const f32x4*)(sp + 4);
;         const float ccv[8] = {c0.x, c0.y, c0.z, c0.w, c1.x, c1.y, c1.z, c1.w}, snv[8] = {s0.x, s0.y, s0.z, s0.w, s1.x, s1.y, s1.z, s1.w};
; __device__ __forceinline__ void p2b_prep(const Params& p, LAS unsigned char* lds, int l, int tid, int lane, int wave, int G) {
;     ...
;     { const bf16* PROJ = (const bf16*)(p.ws + WS_PROJ);
;       const int slot = (lane >> 3) & 3, kcol = (slot >> 1) * 2048 + 384 + 64 * (slot & 1) + 8 * (lane & 7);
;       for (int i0 = gw; i0 < MTOT / 2; i0 += 4 * ngw) {
;           u32x4 raw[4];
; #pragma unroll
;           for (int q = 0; q < 4; ++q) { const int i = i0 + q * ngw; if (i < MTOT / 2) raw[q] = *(const u32x4*)(PROJ + (size_t)(2 * i + (lane >> 5)) * INW + kcol); }
.LBB0_254:
	s_and_b64 vcc, exec, s[0:1]
	s_cbranch_vccz .LBB0_393
	v_readlane_b32 s0, v252, 33
	v_readlane_b32 s4, v248, 4
	s_add_i32 s26, s4, s0
	s_cmp_gt_i32 s26, 0x8fff
	v_readlane_b32 s5, v248, 5
	s_cbranch_scc1 .LBB0_278
	v_lshrrev_b32_e32 v0, 3, v148
	s_waitcnt vmcnt(0)
	v_lshlrev_b32_e32 v2, 7, v148
	v_lshlrev_b32_e32 v3, 3, v148
	v_and_b32_e32 v2, 0x800, v2
	v_lshlrev_b32_e32 v0, 6, v0
	v_and_b32_e32 v6, 56, v3
	v_or3_b32 v0, v2, v0, v6
	v_readlane_b32 s0, v252, 20
	v_lshl_or_b32 v0, v0, 1, v179
	v_readlane_b32 s1, v252, 21
	v_and_b32_e32 v2, 2, v186
	v_cmp_eq_u32_e64 s[40:41], 0, v2
	v_lshl_add_u64 v[18:19], s[0:1], 0, v[0:1]
	v_cmp_lt_i32_e64 s[0:1], v168, v167
	s_lshl_b32 s20, s72, 6
	v_and_b32_e32 v0, 16, v186
	v_cndmask_b32_e64 v2, v166, v168, s[0:1]
	v_cmp_lt_i32_e64 s[0:1], v169, v167
	v_lshlrev_b32_e32 v31, 2, v2
	v_cmp_eq_u32_e32 vcc, 0, v0
	v_cndmask_b32_e64 v2, v166, v169, s[0:1]
	v_lshlrev_b32_e32 v32, 2, v2
	v_xor_b32_e32 v2, 4, v166
	v_cmp_lt_i32_e64 s[0:1], v2, v167
	s_ashr_i32 s21, s20, 31
	v_cndmask_b32_e32 v0, v180, v181, vcc
	v_cndmask_b32_e64 v2, v166, v2, s[0:1]
	s_mov_b32 s0, s72
	v_readlane_b32 s64, v249, 19
	v_readlane_b32 s69, v249, 24
	v_readlane_b32 s73, v249, 28
	v_lshlrev_b32_e32 v33, 2, v2
	v_readlane_b32 s68, v249, 23
	v_readlane_b32 s72, v249, 27
	v_mov_b32_e32 v2, s73
	v_mov_b32_e32 v3, s69
	v_cndmask_b32_e32 v3, v2, v3, vcc
	v_mov_b32_e32 v2, s72
	v_mov_b32_e32 v4, s68
	v_cndmask_b32_e32 v2, v2, v4, vcc
	v_lshl_add_u64 v[2:3], s[20:21], 2, v[2:3]
	v_readlane_b32 s20, v251, 0
	v_lshlrev_b32_e32 v4, 2, v6
	v_mov_b32_e32 v5, v1
	v_readlane_b32 s21, v251, 1
	v_lshl_add_u64 v[20:21], v[2:3], 0, v[4:5]
	s_mov_b32 s72, s0
	v_lshl_add_u64 v[2:3], s[20:21], 0, v[0:1]
	v_lshlrev_b32_e32 v0, 1, v6
	v_lshl_add_u64 v[22:23], v[2:3], 0, v[0:1]
	v_lshlrev_b32_e32 v0, 4, v148
	v_readlane_b32 s0, v252, 26
	v_and_b32_e32 v0, 64, v0
	v_readlane_b32 s1, v252, 27
	s_waitcnt lgkmcnt(0)
	s_lshl_b32 s43, s59, 4
	s_mul_i32 s48, s59, 24
	v_lshl_add_u64 v[2:3], s[0:1], 0, v[0:1]
	s_add_i32 s0, s26, s43
	s_lshl_b32 s27, s59, 3
	s_lshl_b32 s44, s0, 1
	s_add_i32 s0, s26, s48
	s_lshl_b32 s49, s0, 1
	s_add_i32 s0, s26, s27
	s_lshl_b32 s50, s0, 1
	v_readlane_b32 s0, v248, 4
	v_readlane_b32 s1, v248, 5
	v_lshlrev_b32_e32 v0, 5, v148
	s_lshl_b32 s0, s0, 1
	v_readlane_b32 s1, v249, 5
	v_lshrrev_b32_e32 v7, 5, v148
	v_and_b32_e32 v0, 32, v0
	s_add_i32 s51, s1, s0
	s_mov_b32 s34, 0
	v_bfe_u32 v30, v148, 3, 1
	s_lshl_b32 s42, s59, 5
	v_lshl_add_u64 v[24:25], v[2:3], 0, v[0:1]
	v_or_b32_e32 v34, s44, v7
	s_lshl_b32 s45, s59, 6
	v_or_b32_e32 v35, s49, v7
	v_or_b32_e32 v36, s50, v7
	v_add_u32_e32 v37, s51, v7
	v_mov_b32_e32 v2, 0
	v_mov_b32_e32 v3, 0
	v_mov_b32_e32 v4, 0
	v_mov_b32_e32 v5, 0
	v_mov_b32_e32 v6, 0
	v_mov_b32_e32 v7, 0
	v_mov_b32_e32 v8, 0
	v_mov_b32_e32 v9, 0
	v_mov_b32_e32 v10, 0
	v_mov_b32_e32 v11, 0
	v_mov_b32_e32 v12, 0
	v_mov_b32_e32 v13, 0
	v_readlane_b32 s65, v249, 20
	v_readlane_b32 s66, v249, 21
	v_readlane_b32 s67, v249, 22
	v_readlane_b32 s70, v249, 25
	v_readlane_b32 s71, v249, 26
	v_readlane_b32 s74, v249, 29
	v_readlane_b32 s75, v249, 30
	v_readlane_b32 s76, v249, 31
	v_readlane_b32 s77, v249, 32
	v_readlane_b32 s78, v249, 33
	v_readlane_b32 s79, v249, 34
	v_readlane_b32 s22, v251, 2
	v_readlane_b32 s23, v251, 3
	v_mad_u64_u32 v[26:27], s[20:21], v37, s29, v[18:19]
	s_mov_b64 s[42:43], 0x1800000
	s_mov_b64 s[44:45], 0x120000
	s_mov_b64 s[64:65], 0x900000
	s_mov_b64 s[48:49], 0x40000
	s_movk_i32 s50, 0x900
	v_and_b32_e32 v34, 0x7ff, v37
	v_mov_b32_e32 v35, 0
	v_lshrrev_b32_e32 v36, 11, v37
	v_lshl_or_b32 v36, v36, 1, v30
	v_add_u32_e32 v38, 0x100, v34
	v_mov_b32_e32 v39, 0
	v_mad_u32_u24 v38, v36, s50, v38
	v_lshlrev_b64 v[28:29], 7, v[38:39]
	v_lshl_add_u64 v[28:29], v[28:29], 0, v[22:23]
	v_lshrrev_b32_e32 v36, 8, v37
	v_lshl_or_b32 v36, v36, 1, v30
	v_and_b32_e32 v38, 0xff, v37
	v_mad_u32_u24 v38, v36, s50, v38
	v_lshlrev_b64 v[32:33], 7, v[38:39]
	v_lshl_add_u64 v[32:33], v[32:33], 0, v[22:23]
	v_lshlrev_b64 v[34:35], 7, v[34:35]
	v_lshl_add_u64 v[34:35], v[34:35], 0, v[24:25]
	global_load_dwordx4 v[40:43], v[20:21], off
	global_load_dwordx4 v[44:47], v[20:21], off offset:16
	global_load_dwordx4 v[48:51], v[34:35], off
	global_load_dwordx4 v[52:55], v[34:35], off offset:16
	v_lshl_add_u64 v[34:35], v[34:35], 0, s[48:49]
	global_load_dwordx4 v[56:59], v[34:35], off
	global_load_dwordx4 v[60:63], v[34:35], off offset:16
	s_waitcnt vmcnt(0)
	v_xor_b32_e32 v145, 0x80000000, v56
	v_cndmask_b32_e64 v56, v56, v145, s[40:41]
	v_xor_b32_e32 v145, 0x80000000, v57
	v_cndmask_b32_e64 v57, v57, v145, s[40:41]
	v_xor_b32_e32 v145, 0x80000000, v58
	v_cndmask_b32_e64 v58, v58, v145, s[40:41]
	v_xor_b32_e32 v145, 0x80000000, v59
	v_cndmask_b32_e64 v59, v59, v145, s[40:41]
	v_xor_b32_e32 v145, 0x80000000, v60
	v_cndmask_b32_e64 v60, v60, v145, s[40:41]
	v_xor_b32_e32 v145, 0x80000000, v61
	v_cndmask_b32_e64 v61, v61, v145, s[40:41]
	v_xor_b32_e32 v145, 0x80000000, v62
	v_cndmask_b32_e64 v62, v62, v145, s[40:41]
	v_xor_b32_e32 v145, 0x80000000, v63
	v_cndmask_b32_e64 v63, v63, v145, s[40:41]
	s_mov_b32 s51, 0
; __device__ __forceinline__ unsigned pk2(float lo, float hi) { f32x2_t v = {lo, hi}; bf16x2_t b = __builtin_convertvector(v, bf16x2_t); return __builtin_bit_cast(unsigned, b); }
; __device__ __forceinline__ void prep_k_pair(const Params& p, int l, int pair, int lane, const u32x4 rawin) {
;     ...
;     float v[8]; unpack8(rawin, v);
;     float ss = 0.f;
; #pragma unroll
;     for (int j = 0; j < 8; ++j) ss += v[j] * v[j];
;     ss += __shfl_xor(ss, 1); ss += __shfl_xor(ss, 2); ss += __shfl_xor(ss, 4);
;     const float rstd = rsqrtf(ss * (1.0f / 64.0f) + 1e-6f);
;     const float* wn = (mixer ? p.kn_c : p.kn_a) + l * 64 + 8 * dc;
;     { const f32x4 w0 = *(const f32x4*)wn, w1 = *(const f32x4*)(wn + 4);
;       v[0] *= rstd * w0.x; v[1] *= rstd * w0.y; v[2] *= rstd * w0.z; v[3] *= rstd * w0.w; v[4] *= rstd * w1.x; v[5] *= rstd * w1.y; v[6] *= rstd * w1.z; v[7] *= rstd * w1.w; }
;     if (!isctx) {
;         const int half = dc >> 2, f0 = 8 * (dc & 1); const bool isA = (dc & 2) == 0;
;         const float* cp = ct + (size_t)t * 32 + half * 16 + f0; const float* sp = cp + 2048 * 32;
;         const f32x4 c0 = *(const f32x4*)cp, c1 = *(const f32x4*)(cp + 4), s0 = *(const f32x4*)sp, s1 = *(const f32x4*)(sp + 4);
;         const float ccv[8] = {c0.x, c0.y, c0.z, c0.w, c1.x, c1.y, c1.z, c1.w}, snv[8] = {s0.x, s0.y, s0.z, s0.w, s1.x, s1.y, s1.z, s1.w};
; #pragma unroll
;         for (int j = 0; j < 8; ++j) { const float pv = __shfl_xor(v[j], 2); v[j] = isA ? v[j] * ccv[j] - pv * snv[j] : v[j] * ccv[j] + pv * snv[j]; }
;     }
;     u32x4 o; o.x = pk2(v[0], v[1]); o.y = pk2(v[2], v[3]); o.z = pk2(v[4], v[5]); o.w = pk2(v[6], v[7]);
;     bf16* dst = (bf16*)(p.ws + (mixer ? WS_KC : WS_KA)) + ((size_t)(b * 2 + hh) * KEYS + pos) * 64;
;     *(u32x4*)(dst + 8 * dc) = o;
.Lkprep_loop:
	global_load_dwordx4 v[64:67], v[26:27], off
	v_lshl_add_u64 v[26:27], v[26:27], 0, s[42:43]
	global_load_dwordx4 v[68:71], v[26:27], off
	v_lshl_add_u64 v[26:27], v[26:27], 0, s[42:43]
	global_load_dwordx4 v[72:75], v[26:27], off
	v_lshl_add_u64 v[26:27], v[26:27], 0, s[42:43]
	global_load_dwordx4 v[76:79], v[26:27], off
	v_lshl_add_u64 v[26:27], v[26:27], 0, s[42:43]
	s_waitcnt vmcnt(3)
	v_lshlrev_b32_e32 v2, 16, v64
	v_and_b32_e32 v3, 0xffff0000, v64
	v_lshlrev_b32_e32 v4, 16, v65
	v_and_b32_e32 v5, 0xffff0000, v65
	v_lshlrev_b32_e32 v6, 16, v66
	v_and_b32_e32 v7, 0xffff0000, v66
	v_lshlrev_b32_e32 v8, 16, v67
	v_and_b32_e32 v9, 0xffff0000, v67
	v_mul_f32_e32 v144, v2, v2
	v_fmac_f32_e32 v144, v3, v3
	v_fmac_f32_e32 v144, v4, v4
	v_fmac_f32_e32 v144, v5, v5
	v_fmac_f32_e32 v144, v6, v6
	v_fmac_f32_e32 v144, v7, v7
	v_fmac_f32_e32 v144, v8, v8
	v_fmac_f32_e32 v144, v9, v9
	s_nop 1
	v_add_f32_dpp v144, v144, v144 quad_perm:[1,0,3,2] row_mask:0xf bank_mask:0xf
	s_nop 1
	v_add_f32_dpp v144, v144, v144 quad_perm:[2,3,0,1] row_mask:0xf bank_mask:0xf
	s_nop 1
	v_add_f32_dpp v144, v144, v144 row_half_mirror row_mask:0xf bank_mask:0xf
	s_nop 0
	v_fmamk_f32 v144, v144, 0x3c800000, v163
	v_rsq_f32_e32 v144, v144
	s_nop 0
	v_mul_f32_e32 v136, v144, v40
	v_mul_f32_e32 v137, v144, v41
	v_mul_f32_e32 v138, v144, v42
	v_mul_f32_e32 v139, v144, v43
	v_mul_f32_e32 v140, v144, v44
	v_mul_f32_e32 v141, v144, v45
	v_mul_f32_e32 v142, v144, v46
	v_mul_f32_e32 v143, v144, v47
	v_mul_f32_e32 v2, v2, v136
	v_mul_f32_e32 v3, v3, v137
	v_mul_f32_e32 v4, v4, v138
	v_mul_f32_e32 v5, v5, v139
	v_mul_f32_e32 v6, v6, v140
	v_mul_f32_e32 v7, v7, v141
	v_mul_f32_e32 v8, v8, v142
	v_mul_f32_e32 v9, v9, v143
	v_mov_b32_dpp v10, v2 quad_perm:[2,3,0,1] row_mask:0xf bank_mask:0xf
	v_mov_b32_dpp v11, v3 quad_perm:[2,3,0,1] row_mask:0xf bank_mask:0xf
	v_mov_b32_dpp v12, v4 quad_perm:[2,3,0,1] row_mask:0xf bank_mask:0xf
	v_mov_b32_dpp v13, v5 quad_perm:[2,3,0,1] row_mask:0xf bank_mask:0xf
	v_mov_b32_dpp v14, v6 quad_perm:[2,3,0,1] row_mask:0xf bank_mask:0xf
	v_mov_b32_dpp v15, v7 quad_perm:[2,3,0,1] row_mask:0xf bank_mask:0xf
	v_mov_b32_dpp v16, v8 quad_perm:[2,3,0,1] row_mask:0xf bank_mask:0xf
	v_mov_b32_dpp v17, v9 quad_perm:[2,3,0,1] row_mask:0xf bank_mask:0xf
	v_mul_f32_e32 v2, v2, v48
	v_mul_f32_e32 v3, v3, v49
	v_mul_f32_e32 v4, v4, v50
	v_mul_f32_e32 v5, v5, v51
	v_mul_f32_e32 v6, v6, v52
	v_mul_f32_e32 v7, v7, v53
	v_mul_f32_e32 v8, v8, v54
	v_mul_f32_e32 v9, v9, v55
	v_fmac_f32_e32 v2, v10, v56
	v_fmac_f32_e32 v3, v11, v57
	v_fmac_f32_e32 v4, v12, v58
	v_fmac_f32_e32 v5, v13, v59
	v_fmac_f32_e32 v6, v14, v60
	v_fmac_f32_e32 v7, v15, v61
	v_fmac_f32_e32 v8, v16, v62
	v_fmac_f32_e32 v9, v17, v63
	v_lshl_add_u64 v[36:37], v[28:29], 0, s[44:45]
	v_cvt_pk_bf16_f32 v136, v2, v3
	v_cvt_pk_bf16_f32 v137, v4, v5
	v_cvt_pk_bf16_f32 v138, v6, v7
	v_cvt_pk_bf16_f32 v139, v8, v9
	global_store_dwordx4 v[28:29], v[136:139], off
	s_waitcnt vmcnt(2)
	v_lshlrev_b32_e32 v2, 16, v68
	v_and_b32_e32 v3, 0xffff0000, v68
	v_lshlrev_b32_e32 v4, 16, v69
	v_and_b32_e32 v5, 0xffff0000, v69
	v_lshlrev_b32_e32 v6, 16, v70
	v_and_b32_e32 v7, 0xffff0000, v70
	v_lshlrev_b32_e32 v8, 16, v71
	v_and_b32_e32 v9, 0xffff0000, v71
	v_mul_f32_e32 v144, v2, v2
	v_fmac_f32_e32 v144, v3, v3
	v_fmac_f32_e32 v144, v4, v4
	v_fmac_f32_e32 v144, v5, v5
	v_fmac_f32_e32 v144, v6, v6
	v_fmac_f32_e32 v144, v7, v7
	v_fmac_f32_e32 v144, v8, v8
	v_fmac_f32_e32 v144, v9, v9
	s_nop 1
	v_add_f32_dpp v144, v144, v144 quad_perm:[1,0,3,2] row_mask:0xf bank_mask:0xf
	s_nop 1
	v_add_f32_dpp v144, v144, v144 quad_perm:[2,3,0,1] row_mask:0xf bank_mask:0xf
	s_nop 1
	v_add_f32_dpp v144, v144, v144 row_half_mirror row_mask:0xf bank_mask:0xf
	s_nop 0
	v_fmamk_f32 v144, v144, 0x3c800000, v163
	v_rsq_f32_e32 v144, v144
	s_nop 0
	v_mul_f32_e32 v136, v144, v40
	v_mul_f32_e32 v137, v144, v41
	v_mul_f32_e32 v138, v144, v42
	v_mul_f32_e32 v139, v144, v43
	v_mul_f32_e32 v140, v144, v44
	v_mul_f32_e32 v141, v144, v45
	v_mul_f32_e32 v142, v144, v46
	v_mul_f32_e32 v143, v144, v47
	v_mul_f32_e32 v2, v2, v136
	v_mul_f32_e32 v3, v3, v137
	v_mul_f32_e32 v4, v4, v138
	v_mul_f32_e32 v5, v5, v139
	v_mul_f32_e32 v6, v6, v140
	v_mul_f32_e32 v7, v7, v141
	v_mul_f32_e32 v8, v8, v142
	v_mul_f32_e32 v9, v9, v143
	v_mov_b32_dpp v10, v2 quad_perm:[2,3,0,1] row_mask:0xf bank_mask:0xf
	v_mov_b32_dpp v11, v3 quad_perm:[2,3,0,1] row_mask:0xf bank_mask:0xf
	v_mov_b32_dpp v12, v4 quad_perm:[2,3,0,1] row_mask:0xf bank_mask:0xf
	v_mov_b32_dpp v13, v5 quad_perm:[2,3,0,1] row_mask:0xf bank_mask:0xf
	v_mov_b32_dpp v14, v6 quad_perm:[2,3,0,1] row_mask:0xf bank_mask:0xf
	v_mov_b32_dpp v15, v7 quad_perm:[2,3,0,1] row_mask:0xf bank_mask:0xf
	v_mov_b32_dpp v16, v8 quad_perm:[2,3,0,1] row_mask:0xf bank_mask:0xf
	v_mov_b32_dpp v17, v9 quad_perm:[2,3,0,1] row_mask:0xf bank_mask:0xf
	v_mul_f32_e32 v2, v2, v48
	v_mul_f32_e32 v3, v3, v49
	v_mul_f32_e32 v4, v4, v50
	v_mul_f32_e32 v5, v5, v51
	v_mul_f32_e32 v6, v6, v52
	v_mul_f32_e32 v7, v7, v53
	v_mul_f32_e32 v8, v8, v54
	v_mul_f32_e32 v9, v9, v55
	v_fmac_f32_e32 v2, v10, v56
	v_fmac_f32_e32 v3, v11, v57
	v_fmac_f32_e32 v4, v12, v58
	v_fmac_f32_e32 v5, v13, v59
	v_fmac_f32_e32 v6, v14, v60
	v_fmac_f32_e32 v7, v15, v61
	v_fmac_f32_e32 v8, v16, v62
	v_fmac_f32_e32 v9, v17, v63
	v_lshl_add_u64 v[28:29], v[36:37], 0, s[44:45]
	v_cvt_pk_bf16_f32 v136, v2, v3
	v_cvt_pk_bf16_f32 v137, v4, v5
	v_cvt_pk_bf16_f32 v138, v6, v7
	v_cvt_pk_bf16_f32 v139, v8, v9
	global_store_dwordx4 v[36:37], v[136:139], off
	s_waitcnt vmcnt(1)
; __device__ __forceinline__ unsigned pk2(float lo, float hi) { f32x2_t v = {lo, hi}; bf16x2_t b = __builtin_convertvector(v, bf16x2_t); return __builtin_bit_cast(unsigned, b); }
; __device__ __forceinline__ void prep_k_pair(const Params& p, int l, int pair, int lane, const u32x4 rawin) {
;     ...
;     float v[8]; unpack8(rawin, v);
;     float ss = 0.f;
; #pragma unroll
;     for (int j = 0; j < 8; ++j) ss += v[j] * v[j];
;     ss += __shfl_xor(ss, 1); ss += __shfl_xor(ss, 2); ss += __shfl_xor(ss, 4);
;     const float rstd = rsqrtf(ss * (1.0f / 64.0f) + 1e-6f);
;     const float* wn = (mixer ? p.kn_c : p.kn_a) + l * 64 + 8 * dc;
;     { const f32x4 w0 = *(const f32x4*)wn, w1 = *(const f32x4*)(wn + 4);
;       v[0] *= rstd * w0.x; v[1] *= rstd * w0.y; v[2] *= rstd * w0.z; v[3] *= rstd * w0.w; v[4] *= rstd * w1.x; v[5] *= rstd * w1.y; v[6] *= rstd * w1.z; v[7] *= rstd * w1.w; }
;     if (!isctx) {
;         const int half = dc >> 2, f0 = 8 * (dc & 1); const bool isA = (dc & 2) == 0;
;         const float* cp = ct + (size_t)t * 32 + half * 16 + f0; const float* sp = cp + 2048 * 32;
;         const f32x4 c0 = *(const f32x4*)cp, c1 = *(const f32x4*)(cp + 4), s0 = *(const f32x4*)sp, s1 = *(const f32x4*)(sp + 4);
;         const float ccv[8] = {c0.x, c0.y, c0.z, c0.w, c1.x, c1.y, c1.z, c1.w}, snv[8] = {s0.x, s0.y, s0.z, s0.w, s1.x, s1.y, s1.z, s1.w};
; #pragma unroll
;         for (int j = 0; j < 8; ++j) { const float pv = __shfl_xor(v[j], 2); v[j] = isA ? v[j] * ccv[j] - pv * snv[j] : v[j] * ccv[j] + pv * snv[j]; }
;     }
;     u32x4 o; o.x = pk2(v[0], v[1]); o.y = pk2(v[2], v[3]); o.z = pk2(v[4], v[5]); o.w = pk2(v[6], v[7]);
;     bf16* dst = (bf16*)(p.ws + (mixer ? WS_KC : WS_KA)) + ((size_t)(b * 2 + hh) * KEYS + pos) * 64;
;     *(u32x4*)(dst + 8 * dc) = o;
	v_lshlrev_b32_e32 v2, 16, v72
	v_and_b32_e32 v3, 0xffff0000, v72
	v_lshlrev_b32_e32 v4, 16, v73
	v_and_b32_e32 v5, 0xffff0000, v73
	v_lshlrev_b32_e32 v6, 16, v74
	v_and_b32_e32 v7, 0xffff0000, v74
	v_lshlrev_b32_e32 v8, 16, v75
	v_and_b32_e32 v9, 0xffff0000, v75
	v_mul_f32_e32 v144, v2, v2
	v_fmac_f32_e32 v144, v3, v3
	v_fmac_f32_e32 v144, v4, v4
	v_fmac_f32_e32 v144, v5, v5
	v_fmac_f32_e32 v144, v6, v6
	v_fmac_f32_e32 v144, v7, v7
	v_fmac_f32_e32 v144, v8, v8
	v_fmac_f32_e32 v144, v9, v9
	s_nop 1
	v_add_f32_dpp v144, v144, v144 quad_perm:[1,0,3,2] row_mask:0xf bank_mask:0xf
	s_nop 1
	v_add_f32_dpp v144, v144, v144 quad_perm:[2,3,0,1] row_mask:0xf bank_mask:0xf
	s_nop 1
	v_add_f32_dpp v144, v144, v144 row_half_mirror row_mask:0xf bank_mask:0xf
	s_nop 0
	v_fmamk_f32 v144, v144, 0x3c800000, v163
	v_rsq_f32_e32 v144, v144
	s_nop 0
	v_mul_f32_e32 v136, v144, v40
	v_mul_f32_e32 v137, v144, v41
	v_mul_f32_e32 v138, v144, v42
	v_mul_f32_e32 v139, v144, v43
	v_mul_f32_e32 v140, v144, v44
	v_mul_f32_e32 v141, v144, v45
	v_mul_f32_e32 v142, v144, v46
	v_mul_f32_e32 v143, v144, v47
	v_mul_f32_e32 v2, v2, v136
	v_mul_f32_e32 v3, v3, v137
	v_mul_f32_e32 v4, v4, v138
	v_mul_f32_e32 v5, v5, v139
	v_mul_f32_e32 v6, v6, v140
	v_mul_f32_e32 v7, v7, v141
	v_mul_f32_e32 v8, v8, v142
	v_mul_f32_e32 v9, v9, v143
	v_mov_b32_dpp v10, v2 quad_perm:[2,3,0,1] row_mask:0xf bank_mask:0xf
	v_mov_b32_dpp v11, v3 quad_perm:[2,3,0,1] row_mask:0xf bank_mask:0xf
	v_mov_b32_dpp v12, v4 quad_perm:[2,3,0,1] row_mask:0xf bank_mask:0xf
	v_mov_b32_dpp v13, v5 quad_perm:[2,3,0,1] row_mask:0xf bank_mask:0xf
	v_mov_b32_dpp v14, v6 quad_perm:[2,3,0,1] row_mask:0xf bank_mask:0xf
	v_mov_b32_dpp v15, v7 quad_perm:[2,3,0,1] row_mask:0xf bank_mask:0xf
	v_mov_b32_dpp v16, v8 quad_perm:[2,3,0,1] row_mask:0xf bank_mask:0xf
	v_mov_b32_dpp v17, v9 quad_perm:[2,3,0,1] row_mask:0xf bank_mask:0xf
	v_mul_f32_e32 v2, v2, v48
	v_mul_f32_e32 v3, v3, v49
	v_mul_f32_e32 v4, v4, v50
	v_mul_f32_e32 v5, v5, v51
	v_mul_f32_e32 v6, v6, v52
	v_mul_f32_e32 v7, v7, v53
	v_mul_f32_e32 v8, v8, v54
	v_mul_f32_e32 v9, v9, v55
	v_fmac_f32_e32 v2, v10, v56
	v_fmac_f32_e32 v3, v11, v57
	v_fmac_f32_e32 v4, v12, v58
	v_fmac_f32_e32 v5, v13, v59
	v_fmac_f32_e32 v6, v14, v60
	v_fmac_f32_e32 v7, v15, v61
	v_fmac_f32_e32 v8, v16, v62
	v_fmac_f32_e32 v9, v17, v63
	v_lshl_add_u64 v[36:37], v[28:29], 0, s[44:45]
	v_cvt_pk_bf16_f32 v136, v2, v3
	v_cvt_pk_bf16_f32 v137, v4, v5
	v_cvt_pk_bf16_f32 v138, v6, v7
	v_cvt_pk_bf16_f32 v139, v8, v9
	global_store_dwordx4 v[28:29], v[136:139], off
	s_waitcnt vmcnt(0)
	v_lshlrev_b32_e32 v2, 16, v76
	v_and_b32_e32 v3, 0xffff0000, v76
	v_lshlrev_b32_e32 v4, 16, v77
	v_and_b32_e32 v5, 0xffff0000, v77
	v_lshlrev_b32_e32 v6, 16, v78
	v_and_b32_e32 v7, 0xffff0000, v78
	v_lshlrev_b32_e32 v8, 16, v79
	v_and_b32_e32 v9, 0xffff0000, v79
	v_mul_f32_e32 v144, v2, v2
	v_fmac_f32_e32 v144, v3, v3
	v_fmac_f32_e32 v144, v4, v4
	v_fmac_f32_e32 v144, v5, v5
	v_fmac_f32_e32 v144, v6, v6
	v_fmac_f32_e32 v144, v7, v7
	v_fmac_f32_e32 v144, v8, v8
	v_fmac_f32_e32 v144, v9, v9
	s_nop 1
	v_add_f32_dpp v144, v144, v144 quad_perm:[1,0,3,2] row_mask:0xf bank_mask:0xf
	s_nop 1
	v_add_f32_dpp v144, v144, v144 quad_perm:[2,3,0,1] row_mask:0xf bank_mask:0xf
	s_nop 1
	v_add_f32_dpp v144, v144, v144 row_half_mirror row_mask:0xf bank_mask:0xf
	s_nop 0
	v_fmamk_f32 v144, v144, 0x3c800000, v163
	v_rsq_f32_e32 v144, v144
	s_nop 0
	v_mul_f32_e32 v136, v144, v40
	v_mul_f32_e32 v137, v144, v41
	v_mul_f32_e32 v138, v144, v42
	v_mul_f32_e32 v139, v144, v43
	v_mul_f32_e32 v140, v144, v44
	v_mul_f32_e32 v141, v144, v45
	v_mul_f32_e32 v142, v144, v46
	v_mul_f32_e32 v143, v144, v47
	v_mul_f32_e32 v2, v2, v136
	v_mul_f32_e32 v3, v3, v137
	v_mul_f32_e32 v4, v4, v138
	v_mul_f32_e32 v5, v5, v139
	v_mul_f32_e32 v6, v6, v140
	v_mul_f32_e32 v7, v7, v141
	v_mul_f32_e32 v8, v8, v142
	v_mul_f32_e32 v9, v9, v143
	v_mov_b32_dpp v10, v2 quad_perm:[2,3,0,1] row_mask:0xf bank_mask:0xf
	v_mov_b32_dpp v11, v3 quad_perm:[2,3,0,1] row_mask:0xf bank_mask:0xf
	v_mov_b32_dpp v12, v4 quad_perm:[2,3,0,1] row_mask:0xf bank_mask:0xf
	v_mov_b32_dpp v13, v5 quad_perm:[2,3,0,1] row_mask:0xf bank_mask:0xf
	v_mov_b32_dpp v14, v6 quad_perm:[2,3,0,1] row_mask:0xf bank_mask:0xf
	v_mov_b32_dpp v15, v7 quad_perm:[2,3,0,1] row_mask:0xf bank_mask:0xf
	v_mov_b32_dpp v16, v8 quad_perm:[2,3,0,1] row_mask:0xf bank_mask:0xf
	v_mov_b32_dpp v17, v9 quad_perm:[2,3,0,1] row_mask:0xf bank_mask:0xf
	v_mul_f32_e32 v2, v2, v48
	v_mul_f32_e32 v3, v3, v49
	v_mul_f32_e32 v4, v4, v50
	v_mul_f32_e32 v5, v5, v51
	v_mul_f32_e32 v6, v6, v52
	v_mul_f32_e32 v7, v7, v53
	v_mul_f32_e32 v8, v8, v54
	v_mul_f32_e32 v9, v9, v55
	v_fmac_f32_e32 v2, v10, v56
	v_fmac_f32_e32 v3, v11, v57
	v_fmac_f32_e32 v4, v12, v58
	v_fmac_f32_e32 v5, v13, v59
	v_fmac_f32_e32 v6, v14, v60
	v_fmac_f32_e32 v7, v15, v61
	v_fmac_f32_e32 v8, v16, v62
	v_fmac_f32_e32 v9, v17, v63
	v_lshl_add_u64 v[28:29], v[36:37], 0, s[44:45]
	v_cvt_pk_bf16_f32 v136, v2, v3
	v_cvt_pk_bf16_f32 v137, v4, v5
	v_cvt_pk_bf16_f32 v138, v6, v7
	v_cvt_pk_bf16_f32 v139, v8, v9
	global_store_dwordx4 v[36:37], v[136:139], off
	s_add_i32 s51, s51, 1
	s_cmp_lg_u32 s51, 4
	s_cbranch_scc1 .Lkprep_loop
; __device__ __forceinline__ unsigned pk2(float lo, float hi) { f32x2_t v = {lo, hi}; bf16x2_t b = __builtin_convertvector(v, bf16x2_t); return __builtin_bit_cast(unsigned, b); }
; __device__ __forceinline__ void prep_k_pair(const Params& p, int l, int pair, int lane, const u32x4 rawin) {
;     ...
;     float v[8]; unpack8(rawin, v);
;     float ss = 0.f;
; #pragma unroll
;     for (int j = 0; j < 8; ++j) ss += v[j] * v[j];
;     ss += __shfl_xor(ss, 1); ss += __shfl_xor(ss, 2); ss += __shfl_xor(ss, 4);
;     const float rstd = rsqrtf(ss * (1.0f / 64.0f) + 1e-6f);
;     const float* wn = (mixer ? p.kn_c : p.kn_a) + l * 64 + 8 * dc;
;     { const f32x4 w0 = *(const f32x4*)wn, w1 = *(const f32x4*)(wn + 4);
;       v[0] *= rstd * w0.x; v[1] *= rstd * w0.y; v[2] *= rstd * w0.z; v[3] *= rstd * w0.w; v[4] *= rstd * w1.x; v[5] *= rstd * w1.y; v[6] *= rstd * w1.z; v[7] *= rstd * w1.w; }
;     ...
;     u32x4 o; o.x = pk2(v[0], v[1]); o.y = pk2(v[2], v[3]); o.z = pk2(v[4], v[5]); o.w = pk2(v[6], v[7]);
;     bf16* dst = (bf16*)(p.ws + (mixer ? WS_KC : WS_KA)) + ((size_t)(b * 2 + hh) * KEYS + pos) * 64;
;     *(u32x4*)(dst + 8 * dc) = o;
	global_load_dwordx4 v[64:67], v[26:27], off
	v_lshl_add_u64 v[26:27], v[26:27], 0, s[42:43]
	global_load_dwordx4 v[68:71], v[26:27], off
	v_lshl_add_u64 v[26:27], v[26:27], 0, s[42:43]
	s_waitcnt vmcnt(1)
	v_lshlrev_b32_e32 v2, 16, v64
	v_and_b32_e32 v3, 0xffff0000, v64
	v_lshlrev_b32_e32 v4, 16, v65
	v_and_b32_e32 v5, 0xffff0000, v65
	v_lshlrev_b32_e32 v6, 16, v66
	v_and_b32_e32 v7, 0xffff0000, v66
	v_lshlrev_b32_e32 v8, 16, v67
	v_and_b32_e32 v9, 0xffff0000, v67
	v_mul_f32_e32 v144, v2, v2
	v_fmac_f32_e32 v144, v3, v3
	v_fmac_f32_e32 v144, v4, v4
	v_fmac_f32_e32 v144, v5, v5
	v_fmac_f32_e32 v144, v6, v6
	v_fmac_f32_e32 v144, v7, v7
	v_fmac_f32_e32 v144, v8, v8
	v_fmac_f32_e32 v144, v9, v9
	s_nop 1
	v_add_f32_dpp v144, v144, v144 quad_perm:[1,0,3,2] row_mask:0xf bank_mask:0xf
	s_nop 1
	v_add_f32_dpp v144, v144, v144 quad_perm:[2,3,0,1] row_mask:0xf bank_mask:0xf
	s_nop 1
	v_add_f32_dpp v144, v144, v144 row_half_mirror row_mask:0xf bank_mask:0xf
	s_nop 0
	v_fmamk_f32 v144, v144, 0x3c800000, v163
	v_rsq_f32_e32 v144, v144
	s_nop 0
	v_mul_f32_e32 v136, v144, v40
	v_mul_f32_e32 v137, v144, v41
	v_mul_f32_e32 v138, v144, v42
	v_mul_f32_e32 v139, v144, v43
	v_mul_f32_e32 v140, v144, v44
	v_mul_f32_e32 v141, v144, v45
	v_mul_f32_e32 v142, v144, v46
	v_mul_f32_e32 v143, v144, v47
	v_mul_f32_e32 v2, v2, v136
	v_mul_f32_e32 v3, v3, v137
	v_mul_f32_e32 v4, v4, v138
	v_mul_f32_e32 v5, v5, v139
	v_mul_f32_e32 v6, v6, v140
	v_mul_f32_e32 v7, v7, v141
	v_mul_f32_e32 v8, v8, v142
	v_mul_f32_e32 v9, v9, v143
	v_lshl_add_u64 v[38:39], v[32:33], 0, s[64:65]
	v_cvt_pk_bf16_f32 v136, v2, v3
	v_cvt_pk_bf16_f32 v137, v4, v5
	v_cvt_pk_bf16_f32 v138, v6, v7
	v_cvt_pk_bf16_f32 v139, v8, v9
	global_store_dwordx4 v[32:33], v[136:139], off
	s_waitcnt vmcnt(0)
	v_lshlrev_b32_e32 v2, 16, v68
	v_and_b32_e32 v3, 0xffff0000, v68
	v_lshlrev_b32_e32 v4, 16, v69
	v_and_b32_e32 v5, 0xffff0000, v69
	v_lshlrev_b32_e32 v6, 16, v70
	v_and_b32_e32 v7, 0xffff0000, v70
	v_lshlrev_b32_e32 v8, 16, v71
	v_and_b32_e32 v9, 0xffff0000, v71
	v_mul_f32_e32 v144, v2, v2
	v_fmac_f32_e32 v144, v3, v3
	v_fmac_f32_e32 v144, v4, v4
	v_fmac_f32_e32 v144, v5, v5
	v_fmac_f32_e32 v144, v6, v6
	v_fmac_f32_e32 v144, v7, v7
	v_fmac_f32_e32 v144, v8, v8
	v_fmac_f32_e32 v144, v9, v9
	s_nop 1
	v_add_f32_dpp v144, v144, v144 quad_perm:[1,0,3,2] row_mask:0xf bank_mask:0xf
	s_nop 1
	v_add_f32_dpp v144, v144, v144 quad_perm:[2,3,0,1] row_mask:0xf bank_mask:0xf
	s_nop 1
	v_add_f32_dpp v144, v144, v144 row_half_mirror row_mask:0xf bank_mask:0xf
	s_nop 0
	v_fmamk_f32 v144, v144, 0x3c800000, v163
	v_rsq_f32_e32 v144, v144
	s_nop 0
	v_mul_f32_e32 v136, v144, v40
	v_mul_f32_e32 v137, v144, v41
	v_mul_f32_e32 v138, v144, v42
	v_mul_f32_e32 v139, v144, v43
	v_mul_f32_e32 v140, v144, v44
	v_mul_f32_e32 v141, v144, v45
	v_mul_f32_e32 v142, v144, v46
	v_mul_f32_e32 v143, v144, v47
	v_mul_f32_e32 v2, v2, v136
	v_mul_f32_e32 v3, v3, v137
	v_mul_f32_e32 v4, v4, v138
	v_mul_f32_e32 v5, v5, v139
	v_mul_f32_e32 v6, v6, v140
	v_mul_f32_e32 v7, v7, v141
	v_mul_f32_e32 v8, v8, v142
	v_mul_f32_e32 v9, v9, v143
	v_lshl_add_u64 v[32:33], v[38:39], 0, s[64:65]
	v_cvt_pk_bf16_f32 v136, v2, v3
	v_cvt_pk_bf16_f32 v137, v4, v5
	v_cvt_pk_bf16_f32 v138, v6, v7
	v_cvt_pk_bf16_f32 v139, v8, v9
	global_store_dwordx4 v[38:39], v[136:139], off
	s_branch .LBB0_278
